# In1 epilogue fox q/k tiles: second gain-load pair issued with the first (no per-row wait behind the row store)
# baseline (speedup 1.0000x reference)
; __device__ __forceinline__ void store8(bf16_t* p, f32x4 a, f32x4 b) { u32x4 w; w.x = pk2(a.x, a.y); w.y = pk2(a.z, a.w); w.z = pk2(b.x, b.y); w.w = pk2(b.z, b.w); *(u32x4*)p = w; }
; __device__ __forceinline__ float dot4(f32x4 a) { return (a.x * a.x + a.y * a.y) + (a.z * a.z + a.w * a.w); }
;     __device__ __forceinline__ void operator()(AccT& acc, const Unit& u, int wr, int wc, int fr, int fq, LAS unsigned char*) const {
;     ...
;                     float ss = 0.f;
; #pragma unroll
;                     for (int bj = 0; bj < 2; ++bj)
; #pragma unroll
;                         for (int n = 0; n < 2; ++n) ss += dot4(v[bj][n]);
;                     ss = red_fq(ss);
;                     const float rh = rsqrtf(ss * (1.f / 64.f) + EPS) * (u.pn == 3 ? 0.125f * LOG2E : 1.f);
;                     const float* gg = (u.pn == 3) ? gq_fox : gk_fox; bf16_t* dst = ((u.pn == 3) ? qf : kf) + row * 256 + wc * 64 + 8 * fq;
; #pragma unroll
;                     for (int bj = 0; bj < 2; ++bj) { const f32x4 g0 = *(const f32x4*)(gg + 32 * bj + 8 * fq), g1 = *(const f32x4*)(gg + 32 * bj + 8 * fq + 4); store8(dst + 32 * bj, v[bj][0] * g0 * rh, v[bj][1] * g1 * rh); }
.LBB0_668:
	v_mov_b32_e32 v0, 0x3e38aa3b
	v_cndmask_b32_e64 v178, 1.0, v0, s[42:43]
	s_and_b64 vcc, exec, s[78:79]
	v_lshlrev_b32_e32 v0, 1, v134
	v_lshlrev_b32_e32 v171, 2, v134
	s_cbranch_vccz .LBB0_671
	s_and_b64 s[0:1], s[42:43], exec
	s_cselect_b32 s1, s37, s31
	s_cselect_b32 s0, s36, s30
	global_load_dwordx4 v[180:183], v171, s[0:1] offset:16
	global_load_dwordx4 v[184:187], v171, s[0:1]
	global_load_dwordx4 v[200:203], v171, s[0:1] offset:144
	global_load_dwordx4 v[242:245], v171, s[0:1] offset:128
	v_mul_f32_e32 v114, v175, v175
	v_mul_f32_e32 v115, v129, v129
	v_fmac_f32_e32 v114, v174, v174
	v_fmac_f32_e32 v115, v128, v128
	v_add_f32_e32 v114, v114, v115
	v_mul_f32_e32 v115, v127, v127
	v_mul_f32_e32 v176, v125, v125
	v_fmac_f32_e32 v115, v126, v126
	v_fmac_f32_e32 v176, v124, v124
	v_add_f32_e32 v115, v115, v176
	v_add_f32_e32 v114, v114, v115
	v_mul_f32_e32 v115, v123, v123
	v_mul_f32_e32 v176, v121, v121
	v_fmac_f32_e32 v115, v122, v122
	v_fmac_f32_e32 v176, v120, v120
	v_add_f32_e32 v115, v115, v176
	v_add_f32_e32 v114, v115, v114
	v_mul_f32_e32 v115, v119, v119
	v_mul_f32_e32 v176, v117, v117
	v_fmac_f32_e32 v115, v118, v118
	v_fmac_f32_e32 v176, v116, v116
	v_add_f32_e32 v115, v115, v176
	v_add_f32_e32 v114, v115, v114
	v_mov_b32_e32 v115, v114
	s_nop 1
	v_permlane16_swap_b32_e32 v114, v115
	v_add_f32_e32 v114, v114, v115
	v_mov_b32_e32 v115, v114
	s_nop 1
	v_permlane32_swap_b32_e32 v114, v115
	v_add_f32_e32 v114, v114, v115
	v_fmamk_f32 v114, v114, 0x3c800000, v194
	v_cmp_gt_f32_e32 vcc, s33, v114
	v_mul_f32_e32 v115, 0x4b800000, v114
	s_cselect_b32 s9, s59, s61
	v_cndmask_b32_e32 v114, v114, v115, vcc
	v_rsq_f32_e32 v114, v114
	s_cselect_b32 s8, s58, s60
	v_lshlrev_b64 v[176:177], 9, v[156:157]
	v_lshl_add_u64 v[176:177], s[8:9], 0, v[176:177]
	v_mul_f32_e32 v115, 0x45800000, v114
	v_cndmask_b32_e32 v114, v114, v115, vcc
	v_mul_f32_e32 v114, v178, v114
	s_lshl_b32 s2, s86, 1
	v_lshl_add_u64 v[176:177], v[176:177], 0, s[2:3]
	v_lshl_add_u64 v[176:177], v[176:177], 0, v[0:1]
	s_waitcnt vmcnt(3)
	v_pk_mul_f32 v[182:183], v[124:125], v[182:183]
	s_waitcnt vmcnt(2)
	v_pk_mul_f32 v[186:187], v[128:129], v[186:187]
	v_pk_mul_f32 v[184:185], v[174:175], v[184:185]
	v_pk_mul_f32 v[180:181], v[126:127], v[180:181]
	v_pk_mul_f32 v[186:187], v[186:187], v[114:115] op_sel_hi:[1,0]
	v_pk_mul_f32 v[184:185], v[184:185], v[114:115] op_sel_hi:[1,0]
	v_pk_mul_f32 v[188:189], v[182:183], v[114:115] op_sel_hi:[1,0]
	v_pk_mul_f32 v[182:183], v[180:181], v[114:115] op_sel_hi:[1,0]
	v_cvt_pk_bf16_f32 v180, v184, v185
	v_cvt_pk_bf16_f32 v181, v186, v187
	v_cvt_pk_bf16_f32 v182, v182, v183
	v_cvt_pk_bf16_f32 v183, v188, v189
	global_store_dwordx4 v[176:177], v[180:183], off
	s_nop 1
	s_waitcnt vmcnt(1)
	v_mov_b64_e32 v[180:181], v[200:201]
	v_mov_b64_e32 v[182:183], v[202:203]
	s_nop 0
	v_mov_b64_e32 v[184:185], v[242:243]
	v_mov_b64_e32 v[186:187], v[244:245]
	v_pk_mul_f32 v[182:183], v[116:117], v[182:183]
	v_pk_mul_f32 v[186:187], v[120:121], v[186:187]
	v_pk_mul_f32 v[184:185], v[122:123], v[184:185]
	v_pk_mul_f32 v[180:181], v[118:119], v[180:181]
	v_pk_mul_f32 v[186:187], v[186:187], v[114:115] op_sel_hi:[1,0]
	v_pk_mul_f32 v[184:185], v[184:185], v[114:115] op_sel_hi:[1,0]
	v_pk_mul_f32 v[188:189], v[182:183], v[114:115] op_sel_hi:[1,0]
	v_pk_mul_f32 v[114:115], v[180:181], v[114:115] op_sel_hi:[1,0]
	v_cvt_pk_bf16_f32 v180, v184, v185
	v_cvt_pk_bf16_f32 v181, v186, v187
	v_cvt_pk_bf16_f32 v182, v114, v115
	v_cvt_pk_bf16_f32 v183, v188, v189
	global_store_dwordx4 v[176:177], v[180:183], off offset:64
	s_cbranch_execz .LBB0_672

; __device__ __forceinline__ void store8(bf16_t* p, f32x4 a, f32x4 b) { u32x4 w; w.x = pk2(a.x, a.y); w.y = pk2(a.z, a.w); w.z = pk2(b.x, b.y); w.w = pk2(b.z, b.w); *(u32x4*)p = w; }
; __device__ __forceinline__ float dot4(f32x4 a) { return (a.x * a.x + a.y * a.y) + (a.z * a.z + a.w * a.w); }
;     __device__ __forceinline__ void operator()(AccT& acc, const Unit& u, int wr, int wc, int fr, int fq, LAS unsigned char*) const {
;     ...
;                     float ss = 0.f;
; #pragma unroll
;                     for (int bj = 0; bj < 2; ++bj)
; #pragma unroll
;                         for (int n = 0; n < 2; ++n) ss += dot4(v[bj][n]);
;                     ss = red_fq(ss);
;                     const float rh = rsqrtf(ss * (1.f / 64.f) + EPS) * (u.pn == 3 ? 0.125f * LOG2E : 1.f);
;                     const float* gg = (u.pn == 3) ? gq_fox : gk_fox; bf16_t* dst = ((u.pn == 3) ? qf : kf) + row * 256 + wc * 64 + 8 * fq;
; #pragma unroll
;                     for (int bj = 0; bj < 2; ++bj) { const f32x4 g0 = *(const f32x4*)(gg + 32 * bj + 8 * fq), g1 = *(const f32x4*)(gg + 32 * bj + 8 * fq + 4); store8(dst + 32 * bj, v[bj][0] * g0 * rh, v[bj][1] * g1 * rh); }
.LBB0_711:
	s_and_b64 vcc, exec, s[12:13]
	s_cbranch_vccz .LBB0_714
	s_and_b64 s[8:9], s[42:43], exec
	s_cselect_b32 s13, s37, s31
	s_cselect_b32 s12, s36, s30
	global_load_dwordx4 v[124:127], v171, s[12:13] offset:16
	global_load_dwordx4 v[172:175], v171, s[12:13]
	global_load_dwordx4 v[200:203], v171, s[12:13] offset:144
	global_load_dwordx4 v[242:245], v171, s[12:13] offset:128
	v_mul_f32_e32 v115, v111, v111
	v_mul_f32_e32 v120, v113, v113
	v_fmac_f32_e32 v115, v110, v110
	v_fmac_f32_e32 v120, v112, v112
	v_add_f32_e32 v115, v115, v120
	v_mul_f32_e32 v120, v107, v107
	v_mul_f32_e32 v121, v109, v109
	v_fmac_f32_e32 v120, v106, v106
	v_fmac_f32_e32 v121, v108, v108
	v_add_f32_e32 v120, v120, v121
	v_add_f32_e32 v115, v115, v120
	v_mul_f32_e32 v120, v103, v103
	v_mul_f32_e32 v121, v105, v105
	v_fmac_f32_e32 v120, v102, v102
	v_fmac_f32_e32 v121, v104, v104
	v_add_f32_e32 v120, v120, v121
	v_add_f32_e32 v115, v120, v115
	v_mul_f32_e32 v120, v99, v99
	v_mul_f32_e32 v121, v101, v101
	v_fmac_f32_e32 v120, v98, v98
	v_fmac_f32_e32 v121, v100, v100
	v_add_f32_e32 v120, v120, v121
	v_add_f32_e32 v115, v120, v115
	v_mov_b32_e32 v120, v115
	s_nop 1
	v_permlane16_swap_b32_e32 v115, v120
	v_add_f32_e32 v115, v115, v120
	v_mov_b32_e32 v120, v115
	s_nop 1
	v_permlane32_swap_b32_e32 v115, v120
	v_add_f32_e32 v115, v115, v120
	v_fmamk_f32 v115, v115, 0x3c800000, v194
	v_cmp_gt_f32_e32 vcc, s33, v115
	v_mul_f32_e32 v120, 0x4b800000, v115
	s_cselect_b32 s9, s59, s61
	v_cndmask_b32_e32 v115, v115, v120, vcc
	v_rsq_f32_e32 v115, v115
	s_cselect_b32 s8, s58, s60
	v_lshlrev_b64 v[122:123], 9, v[116:117]
	v_lshl_add_u64 v[122:123], s[8:9], 0, v[122:123]
	v_mul_f32_e32 v120, 0x45800000, v115
	v_cndmask_b32_e32 v115, v115, v120, vcc
	v_mul_f32_e32 v120, v178, v115
	s_lshl_b32 s2, s86, 1
	v_lshl_add_u64 v[122:123], v[122:123], 0, s[2:3]
	v_lshl_add_u64 v[122:123], v[122:123], 0, v[0:1]
	s_waitcnt vmcnt(3)
	v_pk_mul_f32 v[126:127], v[108:109], v[126:127]
	s_waitcnt vmcnt(2)
	v_pk_mul_f32 v[128:129], v[112:113], v[174:175]
	v_pk_mul_f32 v[172:173], v[110:111], v[172:173]
	v_pk_mul_f32 v[124:125], v[106:107], v[124:125]
	v_pk_mul_f32 v[128:129], v[128:129], v[120:121] op_sel_hi:[1,0]
	v_pk_mul_f32 v[172:173], v[172:173], v[120:121] op_sel_hi:[1,0]
	v_pk_mul_f32 v[174:175], v[126:127], v[120:121] op_sel_hi:[1,0]
	v_pk_mul_f32 v[126:127], v[124:125], v[120:121] op_sel_hi:[1,0]
	v_cvt_pk_bf16_f32 v124, v172, v173
	v_cvt_pk_bf16_f32 v125, v128, v129
	v_cvt_pk_bf16_f32 v126, v126, v127
	v_cvt_pk_bf16_f32 v127, v174, v175
	global_store_dwordx4 v[122:123], v[124:127], off
	s_nop 1
	s_waitcnt vmcnt(1)
	v_mov_b64_e32 v[124:125], v[200:201]
	v_mov_b64_e32 v[126:127], v[202:203]
	s_nop 0
	v_mov_b64_e32 v[172:173], v[242:243]
	v_mov_b64_e32 v[174:175], v[244:245]
	v_pk_mul_f32 v[126:127], v[100:101], v[126:127]
	v_pk_mul_f32 v[128:129], v[104:105], v[174:175]
	v_pk_mul_f32 v[172:173], v[102:103], v[172:173]
	v_pk_mul_f32 v[124:125], v[98:99], v[124:125]
	v_pk_mul_f32 v[128:129], v[128:129], v[120:121] op_sel_hi:[1,0]
	v_pk_mul_f32 v[172:173], v[172:173], v[120:121] op_sel_hi:[1,0]
	v_pk_mul_f32 v[174:175], v[126:127], v[120:121] op_sel_hi:[1,0]
	v_pk_mul_f32 v[120:121], v[124:125], v[120:121] op_sel_hi:[1,0]
	v_cvt_pk_bf16_f32 v124, v172, v173
	v_cvt_pk_bf16_f32 v125, v128, v129
	v_cvt_pk_bf16_f32 v126, v120, v121
	v_cvt_pk_bf16_f32 v127, v174, v175
	global_store_dwordx4 v[122:123], v[124:127], off offset:64
	s_cbranch_execz .LBB0_715

; __device__ __forceinline__ void store8(bf16_t* p, f32x4 a, f32x4 b) { u32x4 w; w.x = pk2(a.x, a.y); w.y = pk2(a.z, a.w); w.z = pk2(b.x, b.y); w.w = pk2(b.z, b.w); *(u32x4*)p = w; }
; __device__ __forceinline__ float dot4(f32x4 a) { return (a.x * a.x + a.y * a.y) + (a.z * a.z + a.w * a.w); }
;     __device__ __forceinline__ void operator()(AccT& acc, const Unit& u, int wr, int wc, int fr, int fq, LAS unsigned char*) const {
;     ...
;                     float ss = 0.f;
; #pragma unroll
;                     for (int bj = 0; bj < 2; ++bj)
; #pragma unroll
;                         for (int n = 0; n < 2; ++n) ss += dot4(v[bj][n]);
;                     ss = red_fq(ss);
;                     const float rh = rsqrtf(ss * (1.f / 64.f) + EPS) * (u.pn == 3 ? 0.125f * LOG2E : 1.f);
;                     const float* gg = (u.pn == 3) ? gq_fox : gk_fox; bf16_t* dst = ((u.pn == 3) ? qf : kf) + row * 256 + wc * 64 + 8 * fq;
; #pragma unroll
;                     for (int bj = 0; bj < 2; ++bj) { const f32x4 g0 = *(const f32x4*)(gg + 32 * bj + 8 * fq), g1 = *(const f32x4*)(gg + 32 * bj + 8 * fq + 4); store8(dst + 32 * bj, v[bj][0] * g0 * rh, v[bj][1] * g1 * rh); }
.LBB0_754:
	s_and_b64 vcc, exec, s[78:79]
	s_cbranch_vccz .LBB0_757
	s_and_b64 s[0:1], s[42:43], exec
	s_cselect_b32 s1, s37, s31
	s_cselect_b32 s0, s36, s30
	global_load_dwordx4 v[108:111], v171, s[0:1] offset:16
	global_load_dwordx4 v[116:119], v171, s[0:1]
	global_load_dwordx4 v[200:203], v171, s[0:1] offset:144
	global_load_dwordx4 v[242:245], v171, s[0:1] offset:128
	v_mul_f32_e32 v99, v95, v95
	v_mul_f32_e32 v104, v97, v97
	v_fmac_f32_e32 v99, v94, v94
	v_fmac_f32_e32 v104, v96, v96
	v_add_f32_e32 v99, v99, v104
	v_mul_f32_e32 v104, v91, v91
	v_mul_f32_e32 v105, v93, v93
	v_fmac_f32_e32 v104, v90, v90
	v_fmac_f32_e32 v105, v92, v92
	v_add_f32_e32 v104, v104, v105
	v_add_f32_e32 v99, v99, v104
	v_mul_f32_e32 v104, v87, v87
	v_mul_f32_e32 v105, v89, v89
	v_fmac_f32_e32 v104, v86, v86
	v_fmac_f32_e32 v105, v88, v88
	v_add_f32_e32 v104, v104, v105
	v_add_f32_e32 v99, v104, v99
	v_mul_f32_e32 v104, v83, v83
	v_mul_f32_e32 v105, v85, v85
	v_fmac_f32_e32 v104, v82, v82
	v_fmac_f32_e32 v105, v84, v84
	v_add_f32_e32 v104, v104, v105
	v_add_f32_e32 v99, v104, v99
	v_mov_b32_e32 v104, v99
	s_nop 1
	v_permlane16_swap_b32_e32 v99, v104
	v_add_f32_e32 v99, v99, v104
	v_mov_b32_e32 v104, v99
	s_nop 1
	v_permlane32_swap_b32_e32 v99, v104
	v_add_f32_e32 v99, v99, v104
	v_fmamk_f32 v99, v99, 0x3c800000, v194
	v_cmp_gt_f32_e32 vcc, s33, v99
	v_mul_f32_e32 v104, 0x4b800000, v99
	s_cselect_b32 s9, s59, s61
	v_cndmask_b32_e32 v99, v99, v104, vcc
	v_rsq_f32_e32 v99, v99
	s_cselect_b32 s8, s58, s60
	v_lshlrev_b64 v[106:107], 9, v[100:101]
	v_lshl_add_u64 v[106:107], s[8:9], 0, v[106:107]
	v_mul_f32_e32 v104, 0x45800000, v99
	v_cndmask_b32_e32 v99, v99, v104, vcc
	v_mul_f32_e32 v104, v178, v99
	s_lshl_b32 s2, s86, 1
	v_lshl_add_u64 v[106:107], v[106:107], 0, s[2:3]
	v_lshl_add_u64 v[106:107], v[106:107], 0, v[0:1]
	s_waitcnt vmcnt(3)
	v_pk_mul_f32 v[110:111], v[92:93], v[110:111]
	s_waitcnt vmcnt(2)
	v_pk_mul_f32 v[112:113], v[96:97], v[118:119]
	v_pk_mul_f32 v[116:117], v[94:95], v[116:117]
	v_pk_mul_f32 v[108:109], v[90:91], v[108:109]
	v_pk_mul_f32 v[112:113], v[112:113], v[104:105] op_sel_hi:[1,0]
	v_pk_mul_f32 v[116:117], v[116:117], v[104:105] op_sel_hi:[1,0]
	v_pk_mul_f32 v[118:119], v[110:111], v[104:105] op_sel_hi:[1,0]
	v_pk_mul_f32 v[110:111], v[108:109], v[104:105] op_sel_hi:[1,0]
	v_cvt_pk_bf16_f32 v108, v116, v117
	v_cvt_pk_bf16_f32 v109, v112, v113
	v_cvt_pk_bf16_f32 v110, v110, v111
	v_cvt_pk_bf16_f32 v111, v118, v119
	global_store_dwordx4 v[106:107], v[108:111], off
	s_nop 1
	s_waitcnt vmcnt(1)
	v_mov_b64_e32 v[108:109], v[200:201]
	v_mov_b64_e32 v[110:111], v[202:203]
	s_nop 0
	v_mov_b64_e32 v[116:117], v[242:243]
	v_mov_b64_e32 v[118:119], v[244:245]
	v_pk_mul_f32 v[110:111], v[84:85], v[110:111]
	v_pk_mul_f32 v[112:113], v[88:89], v[118:119]
	v_pk_mul_f32 v[116:117], v[86:87], v[116:117]
	v_pk_mul_f32 v[108:109], v[82:83], v[108:109]
	v_pk_mul_f32 v[112:113], v[112:113], v[104:105] op_sel_hi:[1,0]
	v_pk_mul_f32 v[116:117], v[116:117], v[104:105] op_sel_hi:[1,0]
	v_pk_mul_f32 v[118:119], v[110:111], v[104:105] op_sel_hi:[1,0]
	v_pk_mul_f32 v[104:105], v[108:109], v[104:105] op_sel_hi:[1,0]
	v_cvt_pk_bf16_f32 v108, v116, v117
	v_cvt_pk_bf16_f32 v109, v112, v113
	v_cvt_pk_bf16_f32 v110, v104, v105
	v_cvt_pk_bf16_f32 v111, v118, v119
	global_store_dwordx4 v[106:107], v[108:111], off offset:64
	s_cbranch_execz .LBB0_758

; __device__ __forceinline__ void store8(bf16_t* p, f32x4 a, f32x4 b) { u32x4 w; w.x = pk2(a.x, a.y); w.y = pk2(a.z, a.w); w.z = pk2(b.x, b.y); w.w = pk2(b.z, b.w); *(u32x4*)p = w; }
; __device__ __forceinline__ float dot4(f32x4 a) { return (a.x * a.x + a.y * a.y) + (a.z * a.z + a.w * a.w); }
;     __device__ __forceinline__ void operator()(AccT& acc, const Unit& u, int wr, int wc, int fr, int fq, LAS unsigned char*) const {
;     ...
;                     float ss = 0.f;
; #pragma unroll
;                     for (int bj = 0; bj < 2; ++bj)
; #pragma unroll
;                         for (int n = 0; n < 2; ++n) ss += dot4(v[bj][n]);
;                     ss = red_fq(ss);
;                     const float rh = rsqrtf(ss * (1.f / 64.f) + EPS) * (u.pn == 3 ? 0.125f * LOG2E : 1.f);
;                     const float* gg = (u.pn == 3) ? gq_fox : gk_fox; bf16_t* dst = ((u.pn == 3) ? qf : kf) + row * 256 + wc * 64 + 8 * fq;
; #pragma unroll
;                     for (int bj = 0; bj < 2; ++bj) { const f32x4 g0 = *(const f32x4*)(gg + 32 * bj + 8 * fq), g1 = *(const f32x4*)(gg + 32 * bj + 8 * fq + 4); store8(dst + 32 * bj, v[bj][0] * g0 * rh, v[bj][1] * g1 * rh); }
.LBB0_797:
	s_and_b64 vcc, exec, s[12:13]
	s_cbranch_vccz .LBB0_800
	s_and_b64 s[8:9], s[42:43], exec
	s_cselect_b32 s13, s37, s31
	s_cselect_b32 s12, s36, s30
	global_load_dwordx4 v[90:93], v171, s[12:13] offset:16
	global_load_dwordx4 v[94:97], v171, s[12:13]
	global_load_dwordx4 v[200:203], v171, s[12:13] offset:144
	global_load_dwordx4 v[242:245], v171, s[12:13] offset:128
	v_mul_f32_e32 v86, v79, v79
	v_mul_f32_e32 v87, v81, v81
	v_fmac_f32_e32 v86, v78, v78
	v_fmac_f32_e32 v87, v80, v80
	v_add_f32_e32 v86, v86, v87
	v_mul_f32_e32 v87, v75, v75
	v_mul_f32_e32 v88, v77, v77
	v_fmac_f32_e32 v87, v74, v74
	v_fmac_f32_e32 v88, v76, v76
	v_add_f32_e32 v87, v87, v88
	v_add_f32_e32 v86, v86, v87
	v_mul_f32_e32 v87, v71, v71
	v_mul_f32_e32 v88, v73, v73
	v_fmac_f32_e32 v87, v70, v70
	v_fmac_f32_e32 v88, v72, v72
	v_add_f32_e32 v87, v87, v88
	v_add_f32_e32 v86, v87, v86
	v_mul_f32_e32 v87, v67, v67
	v_mul_f32_e32 v88, v69, v69
	v_fmac_f32_e32 v87, v66, v66
	v_fmac_f32_e32 v88, v68, v68
	v_add_f32_e32 v87, v87, v88
	v_add_f32_e32 v86, v87, v86
	v_mov_b32_e32 v87, v86
	s_nop 1
	v_permlane16_swap_b32_e32 v86, v87
	v_add_f32_e32 v86, v86, v87
	v_mov_b32_e32 v87, v86
	s_nop 1
	v_permlane32_swap_b32_e32 v86, v87
	v_add_f32_e32 v86, v86, v87
	v_fmamk_f32 v86, v86, 0x3c800000, v194
	v_cmp_gt_f32_e32 vcc, s33, v86
	v_mul_f32_e32 v87, 0x4b800000, v86
	s_cselect_b32 s9, s59, s61
	v_cndmask_b32_e32 v86, v86, v87, vcc
	v_rsq_f32_e32 v86, v86
	s_cselect_b32 s8, s58, s60
	v_lshlrev_b64 v[88:89], 9, v[82:83]
	v_lshl_add_u64 v[88:89], s[8:9], 0, v[88:89]
	v_mul_f32_e32 v87, 0x45800000, v86
	v_cndmask_b32_e32 v86, v86, v87, vcc
	v_mul_f32_e32 v86, v178, v86
	s_lshl_b32 s2, s86, 1
	v_lshl_add_u64 v[88:89], v[88:89], 0, s[2:3]
	v_lshl_add_u64 v[88:89], v[88:89], 0, v[0:1]
	s_waitcnt vmcnt(3)
	v_pk_mul_f32 v[92:93], v[76:77], v[92:93]
	s_waitcnt vmcnt(2)
	v_pk_mul_f32 v[96:97], v[80:81], v[96:97]
	v_pk_mul_f32 v[94:95], v[78:79], v[94:95]
	v_pk_mul_f32 v[90:91], v[74:75], v[90:91]
	v_pk_mul_f32 v[96:97], v[96:97], v[86:87] op_sel_hi:[1,0]
	v_pk_mul_f32 v[94:95], v[94:95], v[86:87] op_sel_hi:[1,0]
	v_pk_mul_f32 v[98:99], v[92:93], v[86:87] op_sel_hi:[1,0]
	v_pk_mul_f32 v[92:93], v[90:91], v[86:87] op_sel_hi:[1,0]
	v_cvt_pk_bf16_f32 v90, v94, v95
	v_cvt_pk_bf16_f32 v91, v96, v97
	v_cvt_pk_bf16_f32 v92, v92, v93
	v_cvt_pk_bf16_f32 v93, v98, v99
	global_store_dwordx4 v[88:89], v[90:93], off
	s_nop 1
	s_waitcnt vmcnt(1)
	v_mov_b64_e32 v[90:91], v[200:201]
	v_mov_b64_e32 v[92:93], v[202:203]
	s_nop 0
	v_mov_b64_e32 v[94:95], v[242:243]
	v_mov_b64_e32 v[96:97], v[244:245]
	v_pk_mul_f32 v[92:93], v[68:69], v[92:93]
	v_pk_mul_f32 v[96:97], v[72:73], v[96:97]
	v_pk_mul_f32 v[94:95], v[70:71], v[94:95]
	v_pk_mul_f32 v[90:91], v[66:67], v[90:91]
	v_pk_mul_f32 v[96:97], v[96:97], v[86:87] op_sel_hi:[1,0]
	v_pk_mul_f32 v[94:95], v[94:95], v[86:87] op_sel_hi:[1,0]
	v_pk_mul_f32 v[98:99], v[92:93], v[86:87] op_sel_hi:[1,0]
	v_pk_mul_f32 v[86:87], v[90:91], v[86:87] op_sel_hi:[1,0]
	v_cvt_pk_bf16_f32 v90, v94, v95
	v_cvt_pk_bf16_f32 v91, v96, v97
	v_cvt_pk_bf16_f32 v92, v86, v87
	v_cvt_pk_bf16_f32 v93, v98, v99
	global_store_dwordx4 v[88:89], v[90:93], off offset:64
	s_cbranch_execz .LBB0_801

; __device__ __forceinline__ void store8(bf16_t* p, f32x4 a, f32x4 b) { u32x4 w; w.x = pk2(a.x, a.y); w.y = pk2(a.z, a.w); w.z = pk2(b.x, b.y); w.w = pk2(b.z, b.w); *(u32x4*)p = w; }
; __device__ __forceinline__ float dot4(f32x4 a) { return (a.x * a.x + a.y * a.y) + (a.z * a.z + a.w * a.w); }
;     __device__ __forceinline__ void operator()(AccT& acc, const Unit& u, int wr, int wc, int fr, int fq, LAS unsigned char*) const {
;     ...
;                     float ss = 0.f;
; #pragma unroll
;                     for (int bj = 0; bj < 2; ++bj)
; #pragma unroll
;                         for (int n = 0; n < 2; ++n) ss += dot4(v[bj][n]);
;                     ss = red_fq(ss);
;                     const float rh = rsqrtf(ss * (1.f / 64.f) + EPS) * (u.pn == 3 ? 0.125f * LOG2E : 1.f);
;                     const float* gg = (u.pn == 3) ? gq_fox : gk_fox; bf16_t* dst = ((u.pn == 3) ? qf : kf) + row * 256 + wc * 64 + 8 * fq;
; #pragma unroll
;                     for (int bj = 0; bj < 2; ++bj) { const f32x4 g0 = *(const f32x4*)(gg + 32 * bj + 8 * fq), g1 = *(const f32x4*)(gg + 32 * bj + 8 * fq + 4); store8(dst + 32 * bj, v[bj][0] * g0 * rh, v[bj][1] * g1 * rh); }
.LBB0_840:
	s_and_b64 vcc, exec, s[78:79]
	s_cbranch_vccz .LBB0_843
	s_and_b64 s[0:1], s[42:43], exec
	s_cselect_b32 s1, s37, s31
	s_cselect_b32 s0, s36, s30
	global_load_dwordx4 v[76:79], v171, s[0:1] offset:16
	global_load_dwordx4 v[80:83], v171, s[0:1]
	global_load_dwordx4 v[200:203], v171, s[0:1] offset:144
	global_load_dwordx4 v[242:245], v171, s[0:1] offset:128
	v_mul_f32_e32 v67, v63, v63
	v_mul_f32_e32 v72, v65, v65
	v_fmac_f32_e32 v67, v62, v62
	v_fmac_f32_e32 v72, v64, v64
	v_add_f32_e32 v67, v67, v72
	v_mul_f32_e32 v72, v59, v59
	v_mul_f32_e32 v73, v61, v61
	v_fmac_f32_e32 v72, v58, v58
	v_fmac_f32_e32 v73, v60, v60
	v_add_f32_e32 v72, v72, v73
	v_add_f32_e32 v67, v67, v72
	v_mul_f32_e32 v72, v55, v55
	v_mul_f32_e32 v73, v57, v57
	v_fmac_f32_e32 v72, v54, v54
	v_fmac_f32_e32 v73, v56, v56
	v_add_f32_e32 v72, v72, v73
	v_add_f32_e32 v67, v72, v67
	v_mul_f32_e32 v72, v51, v51
	v_mul_f32_e32 v73, v53, v53
	v_fmac_f32_e32 v72, v50, v50
	v_fmac_f32_e32 v73, v52, v52
	v_add_f32_e32 v72, v72, v73
	v_add_f32_e32 v67, v72, v67
	v_mov_b32_e32 v72, v67
	s_nop 1
	v_permlane16_swap_b32_e32 v67, v72
	v_add_f32_e32 v67, v67, v72
	v_mov_b32_e32 v72, v67
	s_nop 1
	v_permlane32_swap_b32_e32 v67, v72
	v_add_f32_e32 v67, v67, v72
	v_fmamk_f32 v67, v67, 0x3c800000, v194
	v_cmp_gt_f32_e32 vcc, s33, v67
	v_mul_f32_e32 v72, 0x4b800000, v67
	s_cselect_b32 s9, s59, s61
	v_cndmask_b32_e32 v67, v67, v72, vcc
	v_rsq_f32_e32 v67, v67
	s_cselect_b32 s8, s58, s60
	v_lshlrev_b64 v[74:75], 9, v[68:69]
	v_lshl_add_u64 v[74:75], s[8:9], 0, v[74:75]
	v_mul_f32_e32 v72, 0x45800000, v67
	v_cndmask_b32_e32 v67, v67, v72, vcc
	v_mul_f32_e32 v72, v178, v67
	s_lshl_b32 s2, s86, 1
	v_lshl_add_u64 v[74:75], v[74:75], 0, s[2:3]
	v_lshl_add_u64 v[74:75], v[74:75], 0, v[0:1]
	s_waitcnt vmcnt(3)
	v_pk_mul_f32 v[78:79], v[60:61], v[78:79]
	s_waitcnt vmcnt(2)
	v_pk_mul_f32 v[82:83], v[64:65], v[82:83]
	v_pk_mul_f32 v[80:81], v[62:63], v[80:81]
	v_pk_mul_f32 v[76:77], v[58:59], v[76:77]
	v_pk_mul_f32 v[82:83], v[82:83], v[72:73] op_sel_hi:[1,0]
	v_pk_mul_f32 v[80:81], v[80:81], v[72:73] op_sel_hi:[1,0]
	v_pk_mul_f32 v[84:85], v[78:79], v[72:73] op_sel_hi:[1,0]
	v_pk_mul_f32 v[78:79], v[76:77], v[72:73] op_sel_hi:[1,0]
	v_cvt_pk_bf16_f32 v76, v80, v81
	v_cvt_pk_bf16_f32 v77, v82, v83
	v_cvt_pk_bf16_f32 v78, v78, v79
	v_cvt_pk_bf16_f32 v79, v84, v85
	global_store_dwordx4 v[74:75], v[76:79], off
	s_nop 1
	s_waitcnt vmcnt(1)
	v_mov_b64_e32 v[76:77], v[200:201]
	v_mov_b64_e32 v[78:79], v[202:203]
	s_nop 0
	v_mov_b64_e32 v[80:81], v[242:243]
	v_mov_b64_e32 v[82:83], v[244:245]
	v_pk_mul_f32 v[78:79], v[52:53], v[78:79]
	v_pk_mul_f32 v[82:83], v[56:57], v[82:83]
	v_pk_mul_f32 v[80:81], v[54:55], v[80:81]
	v_pk_mul_f32 v[76:77], v[50:51], v[76:77]
	v_pk_mul_f32 v[82:83], v[82:83], v[72:73] op_sel_hi:[1,0]
	v_pk_mul_f32 v[80:81], v[80:81], v[72:73] op_sel_hi:[1,0]
	v_pk_mul_f32 v[84:85], v[78:79], v[72:73] op_sel_hi:[1,0]
	v_pk_mul_f32 v[72:73], v[76:77], v[72:73] op_sel_hi:[1,0]
	v_cvt_pk_bf16_f32 v76, v80, v81
	v_cvt_pk_bf16_f32 v77, v82, v83
	v_cvt_pk_bf16_f32 v78, v72, v73
	v_cvt_pk_bf16_f32 v79, v84, v85
	global_store_dwordx4 v[74:75], v[76:79], off offset:64
	s_cbranch_execz .LBB0_844

; __device__ __forceinline__ void store8(bf16_t* p, f32x4 a, f32x4 b) { u32x4 w; w.x = pk2(a.x, a.y); w.y = pk2(a.z, a.w); w.z = pk2(b.x, b.y); w.w = pk2(b.z, b.w); *(u32x4*)p = w; }
; __device__ __forceinline__ float dot4(f32x4 a) { return (a.x * a.x + a.y * a.y) + (a.z * a.z + a.w * a.w); }
;     __device__ __forceinline__ void operator()(AccT& acc, const Unit& u, int wr, int wc, int fr, int fq, LAS unsigned char*) const {
;     ...
;                     float ss = 0.f;
; #pragma unroll
;                     for (int bj = 0; bj < 2; ++bj)
; #pragma unroll
;                         for (int n = 0; n < 2; ++n) ss += dot4(v[bj][n]);
;                     ss = red_fq(ss);
;                     const float rh = rsqrtf(ss * (1.f / 64.f) + EPS) * (u.pn == 3 ? 0.125f * LOG2E : 1.f);
;                     const float* gg = (u.pn == 3) ? gq_fox : gk_fox; bf16_t* dst = ((u.pn == 3) ? qf : kf) + row * 256 + wc * 64 + 8 * fq;
; #pragma unroll
;                     for (int bj = 0; bj < 2; ++bj) { const f32x4 g0 = *(const f32x4*)(gg + 32 * bj + 8 * fq), g1 = *(const f32x4*)(gg + 32 * bj + 8 * fq + 4); store8(dst + 32 * bj, v[bj][0] * g0 * rh, v[bj][1] * g1 * rh); }
.LBB0_883:
	s_and_b64 vcc, exec, s[12:13]
	s_cbranch_vccz .LBB0_886
	s_and_b64 s[8:9], s[42:43], exec
	s_cselect_b32 s13, s37, s31
	s_cselect_b32 s12, s36, s30
	global_load_dwordx4 v[58:61], v171, s[12:13] offset:16
	global_load_dwordx4 v[62:65], v171, s[12:13]
	global_load_dwordx4 v[200:203], v171, s[12:13] offset:144
	global_load_dwordx4 v[242:245], v171, s[12:13] offset:128
	v_mul_f32_e32 v54, v47, v47
	v_mul_f32_e32 v55, v49, v49
	v_fmac_f32_e32 v54, v46, v46
	v_fmac_f32_e32 v55, v48, v48
	v_add_f32_e32 v54, v54, v55
	v_mul_f32_e32 v55, v43, v43
	v_mul_f32_e32 v56, v45, v45
	v_fmac_f32_e32 v55, v42, v42
	v_fmac_f32_e32 v56, v44, v44
	v_add_f32_e32 v55, v55, v56
	v_add_f32_e32 v54, v54, v55
	v_mul_f32_e32 v55, v39, v39
	v_mul_f32_e32 v56, v41, v41
	v_fmac_f32_e32 v55, v38, v38
	v_fmac_f32_e32 v56, v40, v40
	v_add_f32_e32 v55, v55, v56
	v_add_f32_e32 v54, v55, v54
	v_mul_f32_e32 v55, v35, v35
	v_mul_f32_e32 v56, v37, v37
	v_fmac_f32_e32 v55, v34, v34
	v_fmac_f32_e32 v56, v36, v36
	v_add_f32_e32 v55, v55, v56
	v_add_f32_e32 v54, v55, v54
	v_mov_b32_e32 v55, v54
	s_nop 1
	v_permlane16_swap_b32_e32 v54, v55
	v_add_f32_e32 v54, v54, v55
	v_mov_b32_e32 v55, v54
	s_nop 1
	v_permlane32_swap_b32_e32 v54, v55
	v_add_f32_e32 v54, v54, v55
	v_fmamk_f32 v54, v54, 0x3c800000, v194
	v_cmp_gt_f32_e32 vcc, s33, v54
	v_mul_f32_e32 v55, 0x4b800000, v54
	s_cselect_b32 s9, s59, s61
	v_cndmask_b32_e32 v54, v54, v55, vcc
	v_rsq_f32_e32 v54, v54
	s_cselect_b32 s8, s58, s60
	v_lshlrev_b64 v[56:57], 9, v[50:51]
	v_lshl_add_u64 v[56:57], s[8:9], 0, v[56:57]
	v_mul_f32_e32 v55, 0x45800000, v54
	v_cndmask_b32_e32 v54, v54, v55, vcc
	v_mul_f32_e32 v54, v178, v54
	s_lshl_b32 s2, s86, 1
	v_lshl_add_u64 v[56:57], v[56:57], 0, s[2:3]
	v_lshl_add_u64 v[56:57], v[56:57], 0, v[0:1]
	s_waitcnt vmcnt(3)
	v_pk_mul_f32 v[60:61], v[44:45], v[60:61]
	s_waitcnt vmcnt(2)
	v_pk_mul_f32 v[64:65], v[48:49], v[64:65]
	v_pk_mul_f32 v[62:63], v[46:47], v[62:63]
	v_pk_mul_f32 v[58:59], v[42:43], v[58:59]
	v_pk_mul_f32 v[64:65], v[64:65], v[54:55] op_sel_hi:[1,0]
	v_pk_mul_f32 v[62:63], v[62:63], v[54:55] op_sel_hi:[1,0]
	v_pk_mul_f32 v[66:67], v[60:61], v[54:55] op_sel_hi:[1,0]
	v_pk_mul_f32 v[60:61], v[58:59], v[54:55] op_sel_hi:[1,0]
	v_cvt_pk_bf16_f32 v58, v62, v63
	v_cvt_pk_bf16_f32 v59, v64, v65
	v_cvt_pk_bf16_f32 v60, v60, v61
	v_cvt_pk_bf16_f32 v61, v66, v67
	global_store_dwordx4 v[56:57], v[58:61], off
	s_nop 1
	s_waitcnt vmcnt(1)
	v_mov_b64_e32 v[58:59], v[200:201]
	v_mov_b64_e32 v[60:61], v[202:203]
	s_nop 0
	v_mov_b64_e32 v[62:63], v[242:243]
	v_mov_b64_e32 v[64:65], v[244:245]
	v_pk_mul_f32 v[60:61], v[36:37], v[60:61]
	v_pk_mul_f32 v[64:65], v[40:41], v[64:65]
	v_pk_mul_f32 v[62:63], v[38:39], v[62:63]
	v_pk_mul_f32 v[58:59], v[34:35], v[58:59]
	v_pk_mul_f32 v[64:65], v[64:65], v[54:55] op_sel_hi:[1,0]
	v_pk_mul_f32 v[62:63], v[62:63], v[54:55] op_sel_hi:[1,0]
	v_pk_mul_f32 v[66:67], v[60:61], v[54:55] op_sel_hi:[1,0]
	v_pk_mul_f32 v[54:55], v[58:59], v[54:55] op_sel_hi:[1,0]
	v_cvt_pk_bf16_f32 v58, v62, v63
	v_cvt_pk_bf16_f32 v59, v64, v65
	v_cvt_pk_bf16_f32 v60, v54, v55
	v_cvt_pk_bf16_f32 v61, v66, v67
	global_store_dwordx4 v[56:57], v[58:61], off offset:64
	s_cbranch_execz .LBB0_887

; __device__ __forceinline__ void store8(bf16_t* p, f32x4 a, f32x4 b) { u32x4 w; w.x = pk2(a.x, a.y); w.y = pk2(a.z, a.w); w.z = pk2(b.x, b.y); w.w = pk2(b.z, b.w); *(u32x4*)p = w; }
; __device__ __forceinline__ float dot4(f32x4 a) { return (a.x * a.x + a.y * a.y) + (a.z * a.z + a.w * a.w); }
;     __device__ __forceinline__ void operator()(AccT& acc, const Unit& u, int wr, int wc, int fr, int fq, LAS unsigned char*) const {
;     ...
;                 } else {
;                     float ss = 0.f;
; #pragma unroll
;                     for (int bj = 0; bj < 2; ++bj)
; #pragma unroll
;                         for (int n = 0; n < 2; ++n) ss += dot4(v[bj][n]);
;                     ss = red_fq(ss);
;                     const float rh = rsqrtf(ss * (1.f / 64.f) + EPS) * (u.pn == 3 ? 0.125f * LOG2E : 1.f);
;                     const float* gg = (u.pn == 3) ? gq_fox : gk_fox; bf16_t* dst = ((u.pn == 3) ? qf : kf) + row * 256 + wc * 64 + 8 * fq;
; #pragma unroll
;                     for (int bj = 0; bj < 2; ++bj) { const f32x4 g0 = *(const f32x4*)(gg + 32 * bj + 8 * fq), g1 = *(const f32x4*)(gg + 32 * bj + 8 * fq + 4); store8(dst + 32 * bj, v[bj][0] * g0 * rh, v[bj][1] * g1 * rh); }
;                 }
.LBB0_926:
	s_and_b64 vcc, exec, s[78:79]
	s_cbranch_vccz .LBB0_929
	s_and_b64 s[0:1], s[42:43], exec
	s_cselect_b32 s1, s37, s31
	s_cselect_b32 s0, s36, s30
	global_load_dwordx4 v[44:47], v171, s[0:1] offset:16
	global_load_dwordx4 v[48:51], v171, s[0:1]
	global_load_dwordx4 v[200:203], v171, s[0:1] offset:144
	global_load_dwordx4 v[242:245], v171, s[0:1] offset:128
	v_mul_f32_e32 v35, v31, v31
	v_mul_f32_e32 v40, v33, v33
	v_fmac_f32_e32 v35, v30, v30
	v_fmac_f32_e32 v40, v32, v32
	v_add_f32_e32 v35, v35, v40
	v_mul_f32_e32 v40, v27, v27
	v_mul_f32_e32 v41, v29, v29
	v_fmac_f32_e32 v40, v26, v26
	v_fmac_f32_e32 v41, v28, v28
	v_add_f32_e32 v40, v40, v41
	v_add_f32_e32 v35, v35, v40
	v_mul_f32_e32 v40, v23, v23
	v_mul_f32_e32 v41, v25, v25
	v_fmac_f32_e32 v40, v22, v22
	v_fmac_f32_e32 v41, v24, v24
	v_add_f32_e32 v40, v40, v41
	v_add_f32_e32 v35, v40, v35
	v_mul_f32_e32 v40, v19, v19
	v_mul_f32_e32 v41, v21, v21
	v_fmac_f32_e32 v40, v18, v18
	v_fmac_f32_e32 v41, v20, v20
	v_add_f32_e32 v40, v40, v41
	v_add_f32_e32 v35, v40, v35
	v_mov_b32_e32 v40, v35
	s_nop 1
	v_permlane16_swap_b32_e32 v35, v40
	v_add_f32_e32 v35, v35, v40
	v_mov_b32_e32 v40, v35
	s_nop 1
	v_permlane32_swap_b32_e32 v35, v40
	v_add_f32_e32 v35, v35, v40
	v_fmamk_f32 v35, v35, 0x3c800000, v194
	v_cmp_gt_f32_e32 vcc, s33, v35
	v_mul_f32_e32 v40, 0x4b800000, v35
	s_cselect_b32 s9, s59, s61
	v_cndmask_b32_e32 v35, v35, v40, vcc
	v_rsq_f32_e32 v35, v35
	s_cselect_b32 s8, s58, s60
	v_lshlrev_b64 v[42:43], 9, v[36:37]
	v_lshl_add_u64 v[42:43], s[8:9], 0, v[42:43]
	v_mul_f32_e32 v40, 0x45800000, v35
	v_cndmask_b32_e32 v35, v35, v40, vcc
	v_mul_f32_e32 v40, v178, v35
	s_lshl_b32 s2, s86, 1
	v_lshl_add_u64 v[42:43], v[42:43], 0, s[2:3]
	v_lshl_add_u64 v[42:43], v[42:43], 0, v[0:1]
	s_waitcnt vmcnt(3)
	v_pk_mul_f32 v[46:47], v[28:29], v[46:47]
	s_waitcnt vmcnt(2)
	v_pk_mul_f32 v[50:51], v[32:33], v[50:51]
	v_pk_mul_f32 v[48:49], v[30:31], v[48:49]
	v_pk_mul_f32 v[44:45], v[26:27], v[44:45]
	v_pk_mul_f32 v[50:51], v[50:51], v[40:41] op_sel_hi:[1,0]
	v_pk_mul_f32 v[48:49], v[48:49], v[40:41] op_sel_hi:[1,0]
	v_pk_mul_f32 v[52:53], v[46:47], v[40:41] op_sel_hi:[1,0]
	v_pk_mul_f32 v[46:47], v[44:45], v[40:41] op_sel_hi:[1,0]
	v_cvt_pk_bf16_f32 v44, v48, v49
	v_cvt_pk_bf16_f32 v45, v50, v51
	v_cvt_pk_bf16_f32 v46, v46, v47
	v_cvt_pk_bf16_f32 v47, v52, v53
	global_store_dwordx4 v[42:43], v[44:47], off
	s_nop 1
	s_waitcnt vmcnt(1)
	v_mov_b64_e32 v[44:45], v[200:201]
	v_mov_b64_e32 v[46:47], v[202:203]
	s_nop 0
	v_mov_b64_e32 v[48:49], v[242:243]
	v_mov_b64_e32 v[50:51], v[244:245]
	v_pk_mul_f32 v[46:47], v[20:21], v[46:47]
	v_pk_mul_f32 v[50:51], v[24:25], v[50:51]
	v_pk_mul_f32 v[48:49], v[22:23], v[48:49]
	v_pk_mul_f32 v[44:45], v[18:19], v[44:45]
	v_pk_mul_f32 v[50:51], v[50:51], v[40:41] op_sel_hi:[1,0]
	v_pk_mul_f32 v[48:49], v[48:49], v[40:41] op_sel_hi:[1,0]
	v_pk_mul_f32 v[52:53], v[46:47], v[40:41] op_sel_hi:[1,0]
	v_pk_mul_f32 v[40:41], v[44:45], v[40:41] op_sel_hi:[1,0]
	v_cvt_pk_bf16_f32 v44, v48, v49
	v_cvt_pk_bf16_f32 v45, v50, v51
	v_cvt_pk_bf16_f32 v46, v40, v41
	v_cvt_pk_bf16_f32 v47, v52, v53
	global_store_dwordx4 v[42:43], v[44:47], off offset:64
	s_mov_b64 s[78:79], 0x400
	s_cbranch_execz .LBB0_930

; __device__ __forceinline__ void store8(bf16_t* p, f32x4 a, f32x4 b) { u32x4 w; w.x = pk2(a.x, a.y); w.y = pk2(a.z, a.w); w.z = pk2(b.x, b.y); w.w = pk2(b.z, b.w); *(u32x4*)p = w; }
; __device__ __forceinline__ float dot4(f32x4 a) { return (a.x * a.x + a.y * a.y) + (a.z * a.z + a.w * a.w); }
;     __device__ __forceinline__ void operator()(AccT& acc, const Unit& u, int wr, int wc, int fr, int fq, LAS unsigned char*) const {
;     ...
;                 } else {
;                     float ss = 0.f;
; #pragma unroll
;                     for (int bj = 0; bj < 2; ++bj)
; #pragma unroll
;                         for (int n = 0; n < 2; ++n) ss += dot4(v[bj][n]);
;                     ss = red_fq(ss);
;                     const float rh = rsqrtf(ss * (1.f / 64.f) + EPS) * (u.pn == 3 ? 0.125f * LOG2E : 1.f);
;                     const float* gg = (u.pn == 3) ? gq_fox : gk_fox; bf16_t* dst = ((u.pn == 3) ? qf : kf) + row * 256 + wc * 64 + 8 * fq;
; #pragma unroll
;                     for (int bj = 0; bj < 2; ++bj) { const f32x4 g0 = *(const f32x4*)(gg + 32 * bj + 8 * fq), g1 = *(const f32x4*)(gg + 32 * bj + 8 * fq + 4); store8(dst + 32 * bj, v[bj][0] * g0 * rh, v[bj][1] * g1 * rh); }
;                 }
.LBB0_969:
	s_and_b64 vcc, exec, s[12:13]
	s_cbranch_vccz .LBB0_972
	s_and_b64 s[8:9], s[42:43], exec
	s_cselect_b32 s13, s37, s31
	s_cselect_b32 s12, s36, s30
	global_load_dwordx4 v[26:29], v171, s[12:13] offset:16
	global_load_dwordx4 v[30:33], v171, s[12:13]
	global_load_dwordx4 v[200:203], v171, s[12:13] offset:144
	global_load_dwordx4 v[242:245], v171, s[12:13] offset:128
	v_mul_f32_e32 v22, v15, v15
	v_mul_f32_e32 v23, v17, v17
	v_fmac_f32_e32 v22, v14, v14
	v_fmac_f32_e32 v23, v16, v16
	v_add_f32_e32 v22, v22, v23
	v_mul_f32_e32 v23, v11, v11
	v_mul_f32_e32 v24, v13, v13
	v_fmac_f32_e32 v23, v10, v10
	v_fmac_f32_e32 v24, v12, v12
	v_add_f32_e32 v23, v23, v24
	v_add_f32_e32 v22, v22, v23
	v_mul_f32_e32 v23, v7, v7
	v_mul_f32_e32 v24, v9, v9
	v_fmac_f32_e32 v23, v6, v6
	v_fmac_f32_e32 v24, v8, v8
	v_add_f32_e32 v23, v23, v24
	v_add_f32_e32 v22, v23, v22
	v_mul_f32_e32 v23, v3, v3
	v_mul_f32_e32 v24, v5, v5
	v_fmac_f32_e32 v23, v2, v2
	v_fmac_f32_e32 v24, v4, v4
	v_add_f32_e32 v23, v23, v24
	v_add_f32_e32 v22, v23, v22
	v_mov_b32_e32 v23, v22
	s_nop 1
	v_permlane16_swap_b32_e32 v22, v23
	v_add_f32_e32 v22, v22, v23
	v_mov_b32_e32 v23, v22
	s_nop 1
	v_permlane32_swap_b32_e32 v22, v23
	v_add_f32_e32 v22, v22, v23
	v_fmamk_f32 v22, v22, 0x3c800000, v194
	v_cmp_gt_f32_e32 vcc, s33, v22
	v_mul_f32_e32 v23, 0x4b800000, v22
	s_cselect_b32 s9, s59, s61
	v_cndmask_b32_e32 v22, v22, v23, vcc
	v_rsq_f32_e32 v22, v22
	s_cselect_b32 s8, s58, s60
	v_lshlrev_b64 v[24:25], 9, v[18:19]
	v_lshl_add_u64 v[24:25], s[8:9], 0, v[24:25]
	v_mul_f32_e32 v23, 0x45800000, v22
	v_cndmask_b32_e32 v22, v22, v23, vcc
	v_mul_f32_e32 v22, v178, v22
	s_lshl_b32 s2, s86, 1
	v_lshl_add_u64 v[24:25], v[24:25], 0, s[2:3]
	v_lshl_add_u64 v[24:25], v[24:25], 0, v[0:1]
	s_waitcnt vmcnt(3)
	v_pk_mul_f32 v[28:29], v[12:13], v[28:29]
	s_waitcnt vmcnt(2)
	v_pk_mul_f32 v[32:33], v[16:17], v[32:33]
	v_pk_mul_f32 v[30:31], v[14:15], v[30:31]
	v_pk_mul_f32 v[26:27], v[10:11], v[26:27]
	v_pk_mul_f32 v[32:33], v[32:33], v[22:23] op_sel_hi:[1,0]
	v_pk_mul_f32 v[30:31], v[30:31], v[22:23] op_sel_hi:[1,0]
	v_pk_mul_f32 v[34:35], v[28:29], v[22:23] op_sel_hi:[1,0]
	v_pk_mul_f32 v[28:29], v[26:27], v[22:23] op_sel_hi:[1,0]
	v_cvt_pk_bf16_f32 v26, v30, v31
	v_cvt_pk_bf16_f32 v27, v32, v33
	v_cvt_pk_bf16_f32 v28, v28, v29
	v_cvt_pk_bf16_f32 v29, v34, v35
	global_store_dwordx4 v[24:25], v[26:29], off
	s_nop 1
	s_waitcnt vmcnt(1)
	v_mov_b64_e32 v[26:27], v[200:201]
	v_mov_b64_e32 v[28:29], v[202:203]
	s_nop 0
	v_mov_b64_e32 v[30:31], v[242:243]
	v_mov_b64_e32 v[32:33], v[244:245]
	v_pk_mul_f32 v[28:29], v[4:5], v[28:29]
	v_pk_mul_f32 v[32:33], v[8:9], v[32:33]
	v_pk_mul_f32 v[30:31], v[6:7], v[30:31]
	v_pk_mul_f32 v[26:27], v[2:3], v[26:27]
	v_pk_mul_f32 v[32:33], v[32:33], v[22:23] op_sel_hi:[1,0]
	v_pk_mul_f32 v[30:31], v[30:31], v[22:23] op_sel_hi:[1,0]
	v_pk_mul_f32 v[34:35], v[28:29], v[22:23] op_sel_hi:[1,0]
	v_pk_mul_f32 v[22:23], v[26:27], v[22:23] op_sel_hi:[1,0]
	v_cvt_pk_bf16_f32 v26, v30, v31
	v_cvt_pk_bf16_f32 v27, v32, v33
	v_cvt_pk_bf16_f32 v28, v22, v23
	v_cvt_pk_bf16_f32 v29, v34, v35
	global_store_dwordx4 v[24:25], v[26:29], off offset:64
	s_cbranch_execz .LBB0_973
